# attention chunk loop rescheduled: bias gathers, K fragments and V^T fragments read into separate registers up front so LDS latencies overlap; same arithmetic
# speedup vs baseline: 1.0080x; 1.0052x over previous
; #define LAS __attribute__((address_space(3)))
; __device__ __forceinline__ f32x4 mfma16(bf16x8 a, bf16x8 b, f32x4 c) { return __builtin_amdgcn_mfma_f32_16x16x32_bf16(a, b, c, 0, 0, 0); }
; __device__ __forceinline__ void lds_barrier() { asm volatile("s_waitcnt lgkmcnt(0)" ::: "memory"); __builtin_amdgcn_s_barrier(); asm volatile("" ::: "memory"); }
; #define ATT_LOAD(jj_) do { const bf16_t* kb_ = zb + (size_t)((c - 8 + (jj_)) * 64 + skey) * ZLD + hp * 128 + spc * 8; \
;         kr[0] = *(const u32x4*)(kb_ + 256); vr[0] = *(const u32x4*)(kb_ + 512); kr[1] = *(const u32x4*)(kb_ + (size_t)32 * ZLD + 256); vr[1] = *(const u32x4*)(kb_ + (size_t)32 * ZLD + 512); } while (0)
; __device__ __forceinline__ void attn_item(const Params& p, int l, int item, LAS unsigned char* lds) {
;     ...
;     for (int jj = jj0; jj <= 8; ++jj) {
;         LAS unsigned char* Kb = lds + (jj & 1) * BUFB; LAS unsigned char* Vb = Kb + KBUF;
;         *(LAS u32x4*)(Kb + skey * KST + spc * 16) = kr[0]; *(LAS u32x4*)(Kb + (skey + 32) * KST + spc * 16) = kr[1];
;         *(LAS u32x4*)(Vb + skey * VST + spc * 16) = vr[0]; *(LAS u32x4*)(Vb + (skey + 32) * VST + spc * 16) = vr[1];
;         if (jj < 8) ATT_LOAD(jj + 1);
;         lds_barrier();
;         f32x4 s[4];
; #pragma unroll
;         for (int kt = 0; kt < 4; ++kt) { const LAS unsigned char* kp = Kb + (kt * 16 + fr) * KST + hh * 128 + fq * 16;
;             s[kt] = mfma16(*(const LAS bf16x8*)kp, qf0, ZERO4); s[kt] = mfma16(*(const LAS bf16x8*)(kp + 64), qf1, s[kt]); }
;         const int base = (8 - jj) * 64 + q0 + fr;
;         float cmax = -1e30f;
; #pragma unroll
;         for (int kt = 0; kt < 4; ++kt)
; #pragma unroll
;             for (int j = 0; j < 4; ++j) { const int dist = base - (kt * 16 + fq * 4 + j); const int idx = (dist < 256 ? dist : 256) + 63;
;                 const float sv = s[kt][j] * (0.125f * LOG2E) + bias_s[hh * 320 + idx]; s[kt][j] = sv; cmax = fmaxf(cmax, sv); }
.LBB0_410:
	s_bitcmp1_b32 s7, 0
	s_cselect_b32 s15, 0x8c00, 0
	v_add3_u32 v44, s15, v55, v54
	s_waitcnt vmcnt(3)
	ds_write_b128 v44, v[12:15]
	v_add3_u32 v44, s15, v59, v54
	s_waitcnt vmcnt(1)
	ds_write_b128 v44, v[20:23]
	v_add3_u32 v44, s15, v60, v54
	ds_write_b128 v44, v[16:19] offset:17408
	v_add3_u32 v44, s15, v61, v54
	s_cmp_eq_u32 s0, s14
	s_waitcnt vmcnt(0)
	ds_write_b128 v44, v[24:27] offset:17408
	s_cbranch_scc1 .LBB0_412
	v_add_co_u32_e32 v16, vcc, 0xfffd4000, v56
	s_nop 1
	v_addc_co_u32_e32 v17, vcc, -1, v57, vcc
	global_load_dwordx4 v[12:15], v[16:17], off offset:-512
	s_nop 0
	global_load_dwordx4 v[16:19], v[16:17], off
	s_nop 0
	global_load_dwordx4 v[20:23], v[56:57], off offset:-512
	global_load_dwordx4 v[24:27], v[56:57], off
.LBB0_412:
	v_add_u32_e32 v69, s15, v62
	v_add3_u32 v87, v69, v52, v65
	v_add3_u32 v69, v69, v64, v66
	v_add_u32_e32 v71, s14, v67
	s_sub_i32 s14, s14, 64
	v_add_u32_e32 v88, 0x200, v71
	v_min_i32_e32 v88, 0x100, v88
	v_lshl_add_u32 v88, v88, 2, v63
	v_add_u32_e32 v89, 0x1ff, v71
	v_min_i32_e32 v89, 0x100, v89
	v_lshl_add_u32 v89, v89, 2, v63
	v_add_u32_e32 v90, 0x1fe, v71
	v_min_i32_e32 v90, 0x100, v90
	v_lshl_add_u32 v90, v90, 2, v63
	v_add_u32_e32 v91, 0x1fd, v71
	v_min_i32_e32 v91, 0x100, v91
	v_lshl_add_u32 v91, v91, 2, v63
	v_add_u32_e32 v92, 0x1f0, v71
	v_min_i32_e32 v92, 0x100, v92
	v_lshl_add_u32 v92, v92, 2, v63
	v_add_u32_e32 v93, 0x1ef, v71
	v_min_i32_e32 v93, 0x100, v93
	v_lshl_add_u32 v93, v93, 2, v63
	v_add_u32_e32 v94, 0x1ee, v71
	v_min_i32_e32 v94, 0x100, v94
	v_lshl_add_u32 v94, v94, 2, v63
	v_add_u32_e32 v95, 0x1ed, v71
	v_min_i32_e32 v95, 0x100, v95
	v_lshl_add_u32 v95, v95, 2, v63
	v_add_u32_e32 v96, 0x1e0, v71
	v_min_i32_e32 v96, 0x100, v96
	v_lshl_add_u32 v96, v96, 2, v63
	v_add_u32_e32 v97, 0x1df, v71
	v_min_i32_e32 v97, 0x100, v97
	v_lshl_add_u32 v97, v97, 2, v63
	v_add_u32_e32 v98, 0x1de, v71
	v_min_i32_e32 v98, 0x100, v98
	v_lshl_add_u32 v98, v98, 2, v63
	v_add_u32_e32 v99, 0x1dd, v71
	v_min_i32_e32 v99, 0x100, v99
	v_lshl_add_u32 v99, v99, 2, v63
	v_add_u32_e32 v100, 0x1d0, v71
	v_min_i32_e32 v100, 0x100, v100
	v_lshl_add_u32 v100, v100, 2, v63
	v_add_u32_e32 v101, 0x1cf, v71
	v_min_i32_e32 v101, 0x100, v101
	v_lshl_add_u32 v101, v101, 2, v63
	v_add_u32_e32 v102, 0x1ce, v71
	v_min_i32_e32 v102, 0x100, v102
	v_lshl_add_u32 v102, v102, 2, v63
	v_add_u32_e32 v103, 0x1cd, v71
	v_min_i32_e32 v103, 0x100, v103
	v_lshl_add_u32 v103, v103, 2, v63
	s_mov_b64 s[16:17], 0x58000
	v_lshl_add_u64 v[56:57], v[56:57], 0, s[16:17]
	v_and_b32_e32 v47, 64, v207
	v_xor_b32_e32 v45, 16, v207
	v_add_u32_e32 v47, 64, v47
	v_cmp_lt_i32_e32 vcc, v45, v47
	v_xor_b32_e32 v46, 32, v207
	s_nop 1
	v_cndmask_b32_e32 v45, v207, v45, vcc
	v_cmp_lt_i32_e32 vcc, v46, v47
	v_lshlrev_b32_e32 v45, 2, v45
	s_nop 1
	v_cndmask_b32_e32 v46, v207, v46, vcc
	v_lshlrev_b32_e32 v46, 2, v46
	s_waitcnt lgkmcnt(0)
	s_barrier
; #define LAS __attribute__((address_space(3)))
; __device__ __forceinline__ unsigned pk2s(float lo, float hi) { unsigned r; asm("s_nop 0\n\tv_cvt_pk_bf16_f32 %0, %1, %2" : "=v"(r) : "v"(lo), "v"(hi)); return r; }
; __device__ __forceinline__ void attn_item(const Params& p, int l, int item, LAS unsigned char* lds) {
;     ...
;         f32x4 s[4];
; #pragma unroll
;         for (int kt = 0; kt < 4; ++kt) { const LAS unsigned char* kp = Kb + (kt * 16 + fr) * KST + hh * 128 + fq * 16;
;             s[kt] = mfma16(*(const LAS bf16x8*)kp, qf0, ZERO4); s[kt] = mfma16(*(const LAS bf16x8*)(kp + 64), qf1, s[kt]); }
;         const int base = (8 - jj) * 64 + q0 + fr;
;         float cmax = -1e30f;
; #pragma unroll
;         for (int kt = 0; kt < 4; ++kt)
; #pragma unroll
;             for (int j = 0; j < 4; ++j) { const int dist = base - (kt * 16 + fq * 4 + j); const int idx = (dist < 256 ? dist : 256) + 63;
;                 const float sv = s[kt][j] * (0.125f * LOG2E) + bias_s[hh * 320 + idx]; s[kt][j] = sv; cmax = fmaxf(cmax, sv); }
;         cmax = fmaxf(cmax, __shfl_xor(cmax, 16)); cmax = fmaxf(cmax, __shfl_xor(cmax, 32));
;         const float mnew = fmaxf(mrun, cmax), alpha = fexp2(mrun - mnew); mrun = mnew;
;         float ps = 0.f;
; #pragma unroll
;         for (int kt = 0; kt < 4; ++kt)
; #pragma unroll
;             for (int j = 0; j < 4; ++j) { const float e = fexp2(s[kt][j] - mnew); s[kt][j] = e; ps += e; }
;         lsum = lsum * alpha + ps;
; #pragma unroll
;         for (int dt = 0; dt < 4; ++dt) o[dt] *= alpha;
; #pragma unroll
;         for (int i = 0; i < 2; ++i) {
;             u32x4 pw; pw.x = pk2s(s[2 * i][0], s[2 * i][1]); pw.y = pk2s(s[2 * i][2], s[2 * i][3]); pw.z = pk2s(s[2 * i + 1][0], s[2 * i + 1][1]); pw.w = pk2s(s[2 * i + 1][2], s[2 * i + 1][3]);
;             const bf16x8 pb = as_bf8(pw);
;             const LAS unsigned char* vp = Vb + (32 * i + 4 * fq + (fr >> 2)) * VST + hh * 128 + (fr & 3) * 8;
; #pragma unroll
;             for (int dt = 0; dt < 4; ++dt) {
;                 const v4i16_t a0 = __builtin_amdgcn_ds_read_tr16_b64_v4i16((LAS v4i16_t*)(vp + dt * 32));
;                 const v4i16_t a1 = __builtin_amdgcn_ds_read_tr16_b64_v4i16((LAS v4i16_t*)(vp + 16 * VST + dt * 32));
;                 const bf16x8 av = __builtin_shufflevector(a0, a1, 0, 1, 2, 3, 4, 5, 6, 7);
;                 o[dt] = mfma16(av, pb, o[dt]); }
;         }
	ds_read_b32 v88, v88 offset:252
	ds_read_b32 v89, v89 offset:252
	ds_read_b32 v90, v90 offset:252
	ds_read_b32 v91, v91 offset:252
	ds_read_b32 v92, v92 offset:252
	ds_read_b32 v93, v93 offset:252
	ds_read_b32 v94, v94 offset:252
	ds_read_b32 v95, v95 offset:252
	ds_read_b32 v96, v96 offset:252
	ds_read_b32 v97, v97 offset:252
	ds_read_b32 v98, v98 offset:252
	ds_read_b32 v99, v99 offset:252
	ds_read_b32 v100, v100 offset:252
	ds_read_b32 v101, v101 offset:252
	ds_read_b32 v102, v102 offset:252
	ds_read_b32 v103, v103 offset:252
	ds_read_b128 v[104:107], v87 offset:0
	ds_read_b128 v[108:111], v87 offset:64
	ds_read_b128 v[112:115], v87 offset:4352
	ds_read_b128 v[116:119], v87 offset:4416
	ds_read_b128 v[120:123], v87 offset:8704
	ds_read_b128 v[124:127], v87 offset:8768
	ds_read_b128 v[128:131], v87 offset:13056
	ds_read_b128 v[132:135], v87 offset:13120
	s_mov_b32 s15, 0xf149f2ca
	s_waitcnt lgkmcnt(7)
	v_mfma_f32_16x16x32_bf16 v[180:183], v[104:107], v[4:7], 0
	s_waitcnt lgkmcnt(6)
	v_mfma_f32_16x16x32_bf16 v[72:75], v[108:111], v[8:11], v[180:183]
	ds_read_b64_tr_b16 v[148:149], v69 offset:17408
	ds_read_b64_tr_b16 v[150:151], v69 offset:22016
	ds_read_b64_tr_b16 v[152:153], v69 offset:17440
	ds_read_b64_tr_b16 v[154:155], v69 offset:22048
	ds_read_b64_tr_b16 v[156:157], v69 offset:17472
	ds_read_b64_tr_b16 v[158:159], v69 offset:22080
	ds_read_b64_tr_b16 v[160:161], v69 offset:17504
	ds_read_b64_tr_b16 v[162:163], v69 offset:22112
	s_waitcnt lgkmcnt(13)
	v_mfma_f32_16x16x32_bf16 v[184:187], v[112:115], v[4:7], 0
	s_waitcnt lgkmcnt(12)
	v_mfma_f32_16x16x32_bf16 v[76:79], v[116:119], v[8:11], v[184:187]
	s_waitcnt lgkmcnt(11)
	v_mfma_f32_16x16x32_bf16 v[188:191], v[120:123], v[4:7], 0
	s_waitcnt lgkmcnt(10)
	v_mfma_f32_16x16x32_bf16 v[48:51], v[124:127], v[8:11], v[188:191]
	s_waitcnt lgkmcnt(9)
	v_mfma_f32_16x16x32_bf16 v[192:195], v[128:131], v[4:7], 0
	s_waitcnt lgkmcnt(8)
	v_mfma_f32_16x16x32_bf16 v[80:83], v[132:135], v[8:11], v[192:195]
	v_fmac_f32_e32 v88, 0x3e38aa3b, v72
	v_fmac_f32_e32 v89, 0x3e38aa3b, v73
	v_fmac_f32_e32 v90, 0x3e38aa3b, v74
	v_fmac_f32_e32 v91, 0x3e38aa3b, v75
	v_fmac_f32_e32 v92, 0x3e38aa3b, v76
	v_fmac_f32_e32 v93, 0x3e38aa3b, v77
	v_fmac_f32_e32 v94, 0x3e38aa3b, v78
	v_fmac_f32_e32 v95, 0x3e38aa3b, v79
	v_fmac_f32_e32 v96, 0x3e38aa3b, v48
	v_fmac_f32_e32 v97, 0x3e38aa3b, v49
	v_fmac_f32_e32 v98, 0x3e38aa3b, v50
	v_fmac_f32_e32 v99, 0x3e38aa3b, v51
	s_nop 7
	v_fmac_f32_e32 v100, 0x3e38aa3b, v80
	v_fmac_f32_e32 v101, 0x3e38aa3b, v81
	v_fmac_f32_e32 v102, 0x3e38aa3b, v82
	v_fmac_f32_e32 v103, 0x3e38aa3b, v83
	v_max3_f32 v196, v88, s15, v89
	v_max3_f32 v196, v196, v90, v91
	v_max3_f32 v196, v196, v92, v93
	v_max3_f32 v196, v196, v94, v95
	v_max3_f32 v196, v196, v96, v97
	v_max3_f32 v196, v196, v98, v99
	v_max3_f32 v196, v196, v100, v101
	v_max3_f32 v196, v196, v102, v103
	ds_bpermute_b32 v197, v45, v196
	s_waitcnt lgkmcnt(0)
	v_max_f32_e32 v197, v197, v197
	v_max_f32_e32 v197, v196, v197
	ds_bpermute_b32 v47, v46, v197
	s_waitcnt lgkmcnt(0)
	v_max3_f32 v47, v70, v197, v47
	ds_read_b64_tr_b16 v[164:165], v69 offset:26624
	ds_read_b64_tr_b16 v[166:167], v69 offset:31232
	ds_read_b64_tr_b16 v[168:169], v69 offset:26656
	ds_read_b64_tr_b16 v[170:171], v69 offset:31264
	ds_read_b64_tr_b16 v[172:173], v69 offset:26688
	ds_read_b64_tr_b16 v[174:175], v69 offset:31296
	ds_read_b64_tr_b16 v[176:177], v69 offset:26720
	ds_read_b64_tr_b16 v[178:179], v69 offset:31328
	v_sub_f32_e32 v70, v70, v47
	v_sub_f32_e32 v88, v88, v47
	v_sub_f32_e32 v89, v89, v47
	v_sub_f32_e32 v90, v90, v47
	v_sub_f32_e32 v91, v91, v47
	v_sub_f32_e32 v92, v92, v47
	v_sub_f32_e32 v93, v93, v47
	v_sub_f32_e32 v94, v94, v47
	v_sub_f32_e32 v95, v95, v47
	v_sub_f32_e32 v96, v96, v47
	v_sub_f32_e32 v97, v97, v47
	v_sub_f32_e32 v98, v98, v47
	v_sub_f32_e32 v99, v99, v47
	v_sub_f32_e32 v100, v100, v47
	v_sub_f32_e32 v101, v101, v47
	v_sub_f32_e32 v102, v102, v47
	v_sub_f32_e32 v103, v103, v47
	v_exp_f32_e32 v44, v70
	v_exp_f32_e32 v88, v88
	v_exp_f32_e32 v89, v89
	v_exp_f32_e32 v90, v90
	v_exp_f32_e32 v91, v91
	v_exp_f32_e32 v92, v92
	v_exp_f32_e32 v93, v93
	v_exp_f32_e32 v94, v94
	v_exp_f32_e32 v95, v95
	v_exp_f32_e32 v96, v96
	v_exp_f32_e32 v97, v97
	v_exp_f32_e32 v98, v98
	v_exp_f32_e32 v99, v99
	v_exp_f32_e32 v100, v100
	v_exp_f32_e32 v101, v101
	v_exp_f32_e32 v102, v102
	v_exp_f32_e32 v103, v103
	v_pk_mul_f32 v[28:29], v[28:29], v[44:45] op_sel_hi:[1,0]
	v_pk_mul_f32 v[30:31], v[30:31], v[44:45] op_sel_hi:[1,0]
	v_pk_mul_f32 v[32:33], v[32:33], v[44:45] op_sel_hi:[1,0]
	v_pk_mul_f32 v[34:35], v[34:35], v[44:45] op_sel_hi:[1,0]
	v_pk_mul_f32 v[36:37], v[36:37], v[44:45] op_sel_hi:[1,0]
	v_pk_mul_f32 v[38:39], v[38:39], v[44:45] op_sel_hi:[1,0]
	v_pk_mul_f32 v[40:41], v[40:41], v[44:45] op_sel_hi:[1,0]
	v_pk_mul_f32 v[42:43], v[42:43], v[44:45] op_sel_hi:[1,0]
	v_add_f32_e32 v48, 0, v88
	v_add_f32_e32 v48, v89, v48
	v_add_f32_e32 v48, v90, v48
	v_add_f32_e32 v48, v91, v48
	v_add_f32_e32 v48, v92, v48
	v_add_f32_e32 v48, v93, v48
	v_add_f32_e32 v48, v94, v48
	v_add_f32_e32 v48, v95, v48
	v_add_f32_e32 v48, v96, v48
	v_add_f32_e32 v48, v97, v48
	v_add_f32_e32 v48, v98, v48
	v_add_f32_e32 v48, v99, v48
	v_add_f32_e32 v48, v100, v48
	v_add_f32_e32 v48, v101, v48
	v_add_f32_e32 v48, v102, v48
	v_add_f32_e32 v48, v103, v48
	v_fmac_f32_e32 v48, v68, v44
	v_cvt_pk_bf16_f32 v198, v88, v89
	v_cvt_pk_bf16_f32 v199, v90, v91
	v_cvt_pk_bf16_f32 v200, v92, v93
	v_cvt_pk_bf16_f32 v201, v94, v95
	v_cvt_pk_bf16_f32 v214, v96, v97
	v_cvt_pk_bf16_f32 v215, v98, v99
	v_cvt_pk_bf16_f32 v216, v100, v101
	v_cvt_pk_bf16_f32 v217, v102, v103
	s_add_i32 s15, s7, 1
	s_waitcnt lgkmcnt(8)
	v_mfma_f32_16x16x32_bf16 v[28:31], v[148:151], v[198:201], v[28:31]
	v_mfma_f32_16x16x32_bf16 v[32:35], v[152:155], v[198:201], v[32:35]
	v_mfma_f32_16x16x32_bf16 v[36:39], v[156:159], v[198:201], v[36:39]
	v_mfma_f32_16x16x32_bf16 v[40:43], v[160:163], v[198:201], v[40:43]
	s_waitcnt lgkmcnt(0)
	v_mfma_f32_16x16x32_bf16 v[28:31], v[164:167], v[214:217], v[28:31]
	v_mfma_f32_16x16x32_bf16 v[32:35], v[168:171], v[214:217], v[32:35]
	v_mfma_f32_16x16x32_bf16 v[36:39], v[172:175], v[214:217], v[36:39]
	v_mfma_f32_16x16x32_bf16 v[40:43], v[176:179], v[214:217], v[40:43]
	s_cmp_lt_u32 s7, 8
	s_cbranch_scc0 .LBB0_425
	v_mov_b32_e32 v70, v47
	v_mov_b32_e32 v68, v48
	s_mov_b32 s7, s15
	s_branch .LBB0_410
